# mixers queue: the 128 long spatial-gate-sample units first, original interleave after, short retention-sample tail
# speedup vs baseline: 1.0079x; 1.0014x over previous
; __device__ __forceinline__ void phase_mixers(const Params& p, LAS unsigned char* lds, int rep) {
;     ...
;     const int u = (int)__builtin_amdgcn_readfirstlane(*slot);
;     if (u >= 2304) break;
;     if (threadIdx.x == 0) nxt = atomicAdd(ctr, 1u);
;     if (u < 128) mix_ret_prompt(p, lds, u);
;     else {
;       const int v = u - 128, g = v / 17, s = v % 17;
;       if (s < 8) mix_ret_sample(p, lds, g * 8 + s);
;       else if (s < 12) mix_ma_sample(p, lds, g * 4 + (s - 8));
;       else if (s < 14) mix_ma_prompt(p, lds, g * 2 + (s - 12));
;       else if (s < 16) mix_sg_prompt(p, lds, g * 2 + (s - 14));
;       else mix_sg_sample(p, lds, g);
.LBB0_193:
	s_add_i32 s29, s42, 0xff80
	s_and_b32 s29, s29, 0xffff
	s_cmpk_lt_u32 s29, 0x80
	s_cbranch_scc0 .Lq_b
	s_mul_i32 s29, s29, 17
	s_add_i32 s29, s29, 16
	s_branch .Lq_done
.Lq_b:
	s_cmpk_lt_u32 s29, 0x680
	s_cbranch_scc0 .Lq_c
	s_sub_i32 s29, s29, 0x80
	s_lshr_b32 s34, s29, 4
	s_and_b32 s35, s29, 15
	s_mul_i32 s34, s34, 17
	s_add_i32 s29, s34, s35
	s_branch .Lq_done
.Lq_c:
	s_cmpk_lt_u32 s29, 0x780
	s_cbranch_scc0 .Lq_d
	s_sub_i32 s29, s29, 0x680
	s_lshr_b32 s34, s29, 3
	s_and_b32 s35, s29, 7
	s_mul_i32 s34, s34, 17
	s_add_i32 s29, s34, s35
	s_add_i32 s29, s29, 0x668
	s_branch .Lq_done
